# phase 5: every other group of eight workgroups runs its sample-segment scan unit before its prompt unit (state write-back bursts no longer coincide)
# speedup vs baseline: 1.0087x; 1.0050x over previous
.LBB0_697:
	s_cmp_lt_i32 s68, 6
	s_cselect_b64 s[6:7], -1, 0
	s_and_b64 s[48:49], s[6:7], s[4:5]
	s_andn2_b64 vcc, exec, s[48:49]
	s_cbranch_vccnz .LBB0_754
	s_cmpk_gt_i32 s2, 0x1ff
	s_cbranch_scc1 .LBB0_754
	v_lshrrev_b32_e32 v83, 8, v1
	s_mov_b32 s5, 0x9600
	v_lshrrev_b32_e32 v2, 1, v1
	v_and_b32_e32 v30, 31, v1
	v_mad_u32_u24 v32, v83, s5, 0
	s_movk_i32 s5, 0x60
	v_bfe_u32 v31, v1, 5, 1
	v_and_or_b32 v38, v2, s5, v30
	v_lshlrev_b32_e32 v134, 4, v31
	s_movk_i32 s8, 0x50
	v_lshlrev_b32_e32 v33, 1, v38
	s_movk_i32 s33, 0x110
	s_movk_i32 s4, 0x100
	v_mad_u32_u24 v135, v38, s8, v32
	v_add_u32_e32 v137, v32, v134
	v_add_u32_e32 v41, v32, v33
	v_mad_u32_u24 v140, v30, s33, v32
	v_lshlrev_b32_e32 v32, 2, v31
	s_add_i32 s42, 0, 0x12c00
	v_cmp_gt_u32_e64 s[4:5], s4, v1
	v_add_u32_e32 v86, s42, v33
	v_xor_b32_e32 v33, 31, v32
	v_cndmask_b32_e64 v143, v33, v32, s[4:5]
	v_or_b32_e32 v33, 2, v32
	v_mov_b32_e32 v2, 0xfffffc00
	v_mov_b32_e32 v3, 0x400
	v_cmp_gt_u32_e64 s[12:13], v33, v30
	v_or_b32_e32 v33, 3, v32
	v_cndmask_b32_e64 v87, v2, v3, s[4:5]
	v_xor_b32_e32 v2, 31, v134
	v_mov_b32_e32 v39, 0xe0
	v_cmp_gt_u32_e64 s[14:15], v33, v30
	v_or_b32_e32 v33, 8, v32
	v_cndmask_b32_e64 v3, v39, 0, s[4:5]
	v_cndmask_b32_e64 v40, v2, v134, s[4:5]
	v_cmp_gt_u32_e64 s[16:17], v33, v30
	v_or_b32_e32 v33, 9, v32
	v_or_b32_e32 v2, v40, v3
	v_cmp_gt_u32_e64 s[18:19], v33, v30
	v_or_b32_e32 v33, 10, v32
	v_lshl_or_b32 v82, v2, 10, v38
	v_cmp_gt_u32_e64 s[20:21], v33, v30
	v_or_b32_e32 v33, 11, v32
	v_add_u32_e32 v84, v82, v87
	v_cmp_gt_u32_e64 s[22:23], v33, v30
	v_or_b32_e32 v33, 16, v32
	v_add_u32_e32 v2, v84, v87
	v_cmp_gt_u32_e64 s[24:25], v33, v30
	v_or_b32_e32 v33, 17, v32
	v_add_u32_e32 v4, v2, v87
	v_cmp_gt_u32_e64 s[26:27], v33, v30
	v_or_b32_e32 v33, 18, v32
	v_add_u32_e32 v6, v4, v87
	v_cmp_gt_u32_e64 s[28:29], v33, v30
	v_or_b32_e32 v33, 19, v32
	v_add_u32_e32 v8, v6, v87
	v_cmp_gt_u32_e64 s[30:31], v33, v30
	v_or_b32_e32 v33, 24, v32
	v_add_u32_e32 v10, v8, v87
	v_cmp_gt_u32_e64 s[34:35], v33, v30
	v_or_b32_e32 v33, 25, v32
	v_add_u32_e32 v12, v10, v87
	v_cmp_gt_u32_e64 s[8:9], v32, v30
	v_cmp_lt_u32_e64 s[10:11], v32, v30
	v_cmp_gt_u32_e64 s[36:37], v33, v30
	v_or_b32_e32 v33, 26, v32
	v_or_b32_e32 v32, 27, v32
	v_mov_b32_e32 v85, 0
	v_add_u32_e32 v14, v12, v87
	v_cmp_gt_u32_e64 s[38:39], v33, v30
	v_cmp_gt_u32_e64 s[40:41], v32, v30
	v_mov_b32_e32 v32, 0x7c00000
	v_mov_b32_e32 v33, 0x5c00000
	v_add_u32_e32 v16, v14, v87
	v_mul_u32_u24_e32 v139, 0x50, v30
	v_mul_u32_u24_e32 v42, 0x110, v30
	v_lshlrev_b32_e32 v30, 3, v1
	v_cndmask_b32_e64 v32, v32, v33, s[4:5]
	v_mov_b32_e32 v33, v85
	v_add_u32_e32 v18, v16, v87
	v_mov_b32_e32 v34, 0xfffffef0
	v_mov_b32_e32 v35, 0x110
	v_and_b32_e32 v44, 0x78, v30
	v_lshl_add_u64 v[88:89], s[66:67], 0, v[32:33]
	v_lshlrev_b32_e32 v32, 2, v38
	v_add_u32_e32 v20, v18, v87
	v_cndmask_b32_e64 v142, v34, v35, s[4:5]
	v_lshlrev_b32_e32 v30, 1, v44
	v_lshl_or_b32 v34, v31, 11, v32
	v_mov_b32_e32 v35, v85
	v_add_u32_e32 v22, v20, v87
	v_cmp_eq_u32_e64 s[6:7], 0, v31
	v_lshlrev_b32_e32 v136, 5, v31
	v_lshlrev_b32_e32 v141, 3, v31
	v_mul_u32_u24_e32 v43, 0x1100, v31
	v_add_u32_e32 v45, s42, v30
	v_lshl_add_u64 v[36:37], s[66:67], 0, v[34:35]
	s_mov_b64 s[42:43], 0x1c00000
	v_cndmask_b32_e64 v31, 0, v39, s[4:5]
	v_add_u32_e32 v24, v22, v87
	s_add_u32 s55, s66, 0x9c00000
	v_lshl_add_u64 v[90:91], v[36:37], 0, s[42:43]
	v_lshl_add_u64 v[32:33], s[66:67], 0, v[32:33]
	s_mov_b64 s[42:43], 0x1b80000
	v_or_b32_e32 v31, v31, v143
	v_mov_b32_e32 v3, v85
	v_add_u32_e32 v26, v24, v87
	v_lshrrev_b32_e32 v159, 4, v1
	s_addc_u32 s57, s67, 0
	v_lshl_add_u64 v[92:93], v[32:33], 0, s[42:43]
	v_mad_u32_u24 v160, v31, s33, v86
	v_lshl_add_u64 v[32:33], s[64:65], 0, v[34:35]
	s_mov_b64 s[42:43], 0x4000000
	v_readlane_b32 s80, v240, 6
	v_mov_b32_e32 v31, v85
	v_mov_b32_e32 v5, v85
	v_mov_b32_e32 v7, v85
	v_mov_b32_e32 v9, v85
	v_mov_b32_e32 v11, v85
	v_mov_b32_e32 v13, v85
	v_mov_b32_e32 v15, v85
	v_mov_b32_e32 v17, v85
	v_mov_b32_e32 v19, v85
	v_mov_b32_e32 v21, v85
	v_mov_b32_e32 v23, v85
	v_mov_b32_e32 v25, v85
	v_mov_b32_e32 v27, v85
	v_add_u32_e32 v28, v26, v87
	v_mov_b32_e32 v29, v85
	v_mul_u32_u24_e32 v46, 0x110, v159
	s_add_u32 s76, s66, 0x3c00000
	v_lshl_add_u64 v[94:95], v[32:33], 0, s[42:43]
	v_lshlrev_b32_e32 v32, 2, v44
	v_mov_b32_e32 v33, v85
	v_readlane_b32 s81, v240, 7
	v_readlane_b32 s82, v240, 8
	v_readlane_b32 s83, v240, 9
	v_readlane_b32 s84, v240, 10
	v_readlane_b32 s85, v240, 11
	v_readlane_b32 s86, v240, 12
	v_readlane_b32 s87, v240, 13
	v_readlane_b32 s88, v240, 14
	v_readlane_b32 s89, v240, 15
	v_readlane_b32 s90, v240, 16
	v_readlane_b32 s91, v240, 17
	v_readlane_b32 s92, v240, 18
	v_readlane_b32 s93, v240, 19
	v_readlane_b32 s94, v240, 20
	v_readlane_b32 s95, v240, 21
	v_lshl_add_u64 v[30:31], s[66:67], 0, v[30:31]
	s_mov_b64 s[42:43], 0xbc00000
	v_lshlrev_b64 v[102:103], 1, v[2:3]
	v_mbcnt_lo_u32_b32 v2, -1, 0
	s_mov_b32 s53, 0
	v_mul_i32_i24_e32 v138, 0xffffffb4, v38
	v_lshlrev_b32_e32 v144, 1, v142
	v_mul_i32_i24_e32 v145, 3, v142
	v_lshlrev_b32_e32 v146, 3, v142
	v_mul_i32_i24_e32 v147, 9, v142
	v_mul_i32_i24_e32 v148, 10, v142
	v_mul_i32_i24_e32 v149, 11, v142
	v_lshlrev_b32_e32 v150, 4, v142
	v_mul_i32_i24_e32 v151, 17, v142
	v_mul_i32_i24_e32 v152, 18, v142
	v_mul_i32_i24_e32 v153, 19, v142
	v_mul_i32_i24_e32 v154, 24, v142
	v_mul_i32_i24_e32 v155, 25, v142
	v_mul_i32_i24_e32 v156, 26, v142
	v_mul_i32_i24_e32 v157, 27, v142
	v_lshlrev_b32_e32 v158, 3, v83
	s_addc_u32 s77, s67, 0
	v_lshl_add_u64 v[96:97], s[82:83], 0, v[32:33]
	v_lshl_add_u64 v[98:99], v[30:31], 0, s[42:43]
	v_lshl_or_b32 v161, v40, 10, v38
	s_movk_i32 s78, 0x2000
	s_movk_i32 s79, 0x3000
	s_movk_i32 s80, 0x4000
	s_movk_i32 s81, 0x5000
	s_movk_i32 s82, 0x6000
	s_movk_i32 s83, 0x7000
	s_mov_b32 s84, 0x8000
	s_mov_b32 s85, 0x9000
	s_mov_b32 s86, 0xa000
	s_mov_b32 s87, 0xb000
	s_mov_b32 s88, 0xc000
	s_mov_b32 s89, 0xd000
	s_mov_b32 s90, 0xe000
	s_mov_b32 s91, 0xf000
	v_add_u32_e32 v162, v45, v46
	s_mov_b32 s92, 0x10000
	s_mov_b32 s93, 0x30000
	s_brev_b32 s54, 60
	s_mov_b32 s56, 0x358637bd
	s_mov_b32 s94, 0x800000
	s_mov_b32 s95, 0x50000
	v_lshlrev_b64 v[100:101], 1, v[84:85]
	v_lshlrev_b64 v[104:105], 1, v[4:5]
	v_lshlrev_b64 v[106:107], 1, v[6:7]
	v_lshlrev_b64 v[108:109], 1, v[8:9]
	v_lshlrev_b64 v[110:111], 1, v[10:11]
	v_lshlrev_b64 v[112:113], 1, v[12:13]
	v_lshlrev_b64 v[114:115], 1, v[14:15]
	v_lshlrev_b64 v[116:117], 1, v[16:17]
	v_lshlrev_b64 v[118:119], 1, v[18:19]
	v_lshlrev_b64 v[120:121], 1, v[20:21]
	v_lshlrev_b64 v[122:123], 1, v[22:23]
	v_lshlrev_b64 v[124:125], 1, v[24:25]
	v_lshlrev_b64 v[126:127], 1, v[26:27]
	v_lshlrev_b64 v[128:129], 1, v[28:29]
	v_mbcnt_hi_u32_b32 v163, -1, v2
	v_add_u32_e32 v164, v41, v43
	v_add_u32_e32 v165, v137, v42
	s_mov_b32 s96, s2
	s_mov_b32 s32, s70
	s_cmpk_lg_u32 s70, 0x100
	s_cbranch_scc1 .Lp5_order
	s_bitcmp1_b32 s2, 3
	s_cbranch_scc0 .Lp5_order
	s_addk_i32 s96, 0x100
	s_movk_i32 s32, 0xff00
.Lp5_order:
	s_branch .LBB0_702
.LBB0_700:
	s_or_b64 exec, exec, s[42:43]
	s_waitcnt lgkmcnt(0)
	s_barrier
	ds_read_b128 v[66:69], v191 offset:8704
	ds_read_b128 v[70:73], v165
	ds_read_b128 v[168:171], v165 offset:32
	ds_read_b128 v[172:175], v191 offset:8736
	s_waitcnt lgkmcnt(2)
	v_mfma_f32_32x32x16_bf16 v[66:81], v[66:69], v[70:73], 0
	s_waitcnt lgkmcnt(0)
	v_mfma_f32_32x32x16_bf16 v[66:81], v[172:175], v[168:171], v[66:81]
	ds_read_b128 v[168:171], v191 offset:8768
	ds_read_b128 v[172:175], v165 offset:64
	s_waitcnt lgkmcnt(0)
	v_mfma_f32_32x32x16_bf16 v[66:81], v[168:171], v[172:175], v[66:81]
	ds_read_b128 v[168:171], v191 offset:8800
	ds_read_b128 v[172:175], v165 offset:96
	s_waitcnt lgkmcnt(0)
	v_mfma_f32_32x32x16_bf16 v[66:81], v[168:171], v[172:175], v[66:81]
	ds_read_b128 v[168:171], v191 offset:8832
	ds_read_b128 v[172:175], v165 offset:128
	s_waitcnt lgkmcnt(0)
	v_mfma_f32_32x32x16_bf16 v[66:81], v[168:171], v[172:175], v[66:81]
	ds_read_b128 v[168:171], v191 offset:8864
	ds_read_b128 v[172:175], v165 offset:160
	s_waitcnt lgkmcnt(0)
	v_mfma_f32_32x32x16_bf16 v[66:81], v[168:171], v[172:175], v[66:81]
	ds_read_b128 v[168:171], v191 offset:8896
	ds_read_b128 v[172:175], v165 offset:192
	s_waitcnt lgkmcnt(0)
	v_mfma_f32_32x32x16_bf16 v[66:81], v[168:171], v[172:175], v[66:81]
	ds_read_b128 v[168:171], v191 offset:8928
	ds_read_b128 v[172:175], v165 offset:224
	ds_read2_b64 v[176:179], v200 offset0:128 offset1:130
	ds_read2_b64 v[180:183], v200 offset0:132 offset1:134
	s_waitcnt lgkmcnt(2)
	v_mfma_f32_32x32x16_bf16 v[66:81], v[168:171], v[172:175], v[66:81]
	v_cvt_pk_bf16_f32 v172, v34, v35
	v_cvt_pk_bf16_f32 v173, v36, v37
	v_cvt_pk_bf16_f32 v174, v38, v39
	v_cvt_pk_bf16_f32 v175, v40, v41
	s_nop 7
	v_cndmask_b32_e64 v84, v66, 0, s[8:9]
	v_cndmask_b32_e64 v130, 0, v67, s[10:11]
	v_cndmask_b32_e64 v67, v68, 0, s[12:13]
	v_cndmask_b32_e64 v68, v69, 0, s[14:15]
	v_cndmask_b32_e64 v69, v70, 0, s[16:17]
	v_cndmask_b32_e64 v70, v71, 0, s[18:19]
	v_cndmask_b32_e64 v71, v72, 0, s[20:21]
	v_cndmask_b32_e64 v72, v73, 0, s[22:23]
	v_cndmask_b32_e64 v66, v84, v66, s[10:11]
	v_cvt_pk_bf16_f32 v67, v67, v68
	v_cvt_pk_bf16_f32 v68, v69, v70
	v_cvt_pk_bf16_f32 v69, v71, v72
	v_cvt_pk_bf16_f32 v66, v66, v130
	v_cndmask_b32_e64 v73, v74, 0, s[24:25]
	v_cndmask_b32_e64 v74, v75, 0, s[26:27]
	v_cndmask_b32_e64 v131, v76, 0, s[28:29]
	v_cndmask_b32_e64 v167, v77, 0, s[30:31]
	v_cndmask_b32_e64 v170, v78, 0, s[34:35]
	v_cndmask_b32_e64 v84, v79, 0, s[36:37]
	v_cndmask_b32_e64 v130, v80, 0, s[38:39]
	v_cndmask_b32_e64 v171, v81, 0, s[40:41]
	v_cvt_pk_bf16_f32 v168, v73, v74
	s_waitcnt lgkmcnt(1)
	v_mfma_f32_32x32x16_bf16 v[66:81], v[66:69], v[176:179], 0
	v_cvt_pk_bf16_f32 v169, v131, v167
	v_cvt_pk_bf16_f32 v170, v170, v84
	v_cvt_pk_bf16_f32 v171, v130, v171
	s_waitcnt lgkmcnt(0)
	s_nop 0
	v_mfma_f32_32x32x16_bf16 v[66:81], v[168:171], v[180:183], v[66:81]
	ds_read2_b64 v[168:171], v189 offset1:2
	s_waitcnt lgkmcnt(0)
	v_mfma_f32_32x32x16_bf16 v[66:81], v[168:171], v[172:175], v[66:81]
	ds_read2_b64 v[168:171], v189 offset0:4 offset1:6
	v_cvt_pk_bf16_f32 v172, v42, v43
	v_cvt_pk_bf16_f32 v173, v44, v45
	v_cvt_pk_bf16_f32 v174, v46, v47
	v_cvt_pk_bf16_f32 v175, v48, v49
	s_waitcnt lgkmcnt(0)
	s_nop 0
	v_mfma_f32_32x32x16_bf16 v[66:81], v[168:171], v[172:175], v[66:81]
	ds_read2_b64 v[168:171], v189 offset0:8 offset1:10
	v_cvt_pk_bf16_f32 v172, v50, v51
	v_cvt_pk_bf16_f32 v173, v52, v53
	v_cvt_pk_bf16_f32 v174, v54, v55
	v_cvt_pk_bf16_f32 v175, v56, v57
	s_waitcnt lgkmcnt(0)
	s_nop 0
	v_mfma_f32_32x32x16_bf16 v[66:81], v[168:171], v[172:175], v[66:81]
	ds_read2_b64 v[168:171], v189 offset0:12 offset1:14
	v_cvt_pk_bf16_f32 v172, v58, v59
	v_cvt_pk_bf16_f32 v173, v60, v61
	v_cvt_pk_bf16_f32 v174, v62, v63
	v_cvt_pk_bf16_f32 v175, v64, v65
	s_waitcnt lgkmcnt(0)
	s_nop 0
	v_mfma_f32_32x32x16_bf16 v[66:81], v[168:171], v[172:175], v[66:81]
	ds_read2_b64 v[168:171], v189 offset0:16 offset1:18
	v_cvt_pk_bf16_f32 v172, v18, v19
	v_cvt_pk_bf16_f32 v173, v20, v21
	v_cvt_pk_bf16_f32 v174, v22, v23
	v_cvt_pk_bf16_f32 v175, v24, v25
	s_waitcnt lgkmcnt(0)
	s_nop 0
	v_mfma_f32_32x32x16_bf16 v[66:81], v[168:171], v[172:175], v[66:81]
	ds_read2_b64 v[168:171], v189 offset0:20 offset1:22
	v_cvt_pk_bf16_f32 v172, v26, v27
	v_cvt_pk_bf16_f32 v173, v28, v29
	v_cvt_pk_bf16_f32 v174, v30, v31
	v_cvt_pk_bf16_f32 v175, v32, v33
	s_waitcnt lgkmcnt(0)
	s_nop 0
	v_mfma_f32_32x32x16_bf16 v[66:81], v[168:171], v[172:175], v[66:81]
	ds_read2_b64 v[168:171], v189 offset0:24 offset1:26
	v_cvt_pk_bf16_f32 v172, v2, v3
	v_cvt_pk_bf16_f32 v173, v4, v5
	v_cvt_pk_bf16_f32 v174, v6, v7
	v_cvt_pk_bf16_f32 v175, v8, v9
	s_waitcnt lgkmcnt(0)
	s_nop 0
	v_mfma_f32_32x32x16_bf16 v[66:81], v[168:171], v[172:175], v[66:81]
	ds_read2_b64 v[168:171], v189 offset0:28 offset1:30
	v_cvt_pk_bf16_f32 v172, v10, v11
	v_cvt_pk_bf16_f32 v173, v12, v13
	v_cvt_pk_bf16_f32 v174, v14, v15
	v_cvt_pk_bf16_f32 v175, v16, v17
	s_waitcnt lgkmcnt(0)
	s_nop 0
	v_mfma_f32_32x32x16_bf16 v[66:81], v[168:171], v[172:175], v[66:81]
	ds_read_u16 v84, v160
	v_add_u32_e32 v130, v160, v142
	s_waitcnt lgkmcnt(0)
	v_lshlrev_b32_e32 v84, 16, v84
	s_nop 7
	v_add_f32_e32 v66, v66, v84
	v_cvt_pk_bf16_f32 v66, v66, s0
	ds_write_b16 v160, v66
	ds_read_u16 v66, v130
	v_add_u32_e32 v84, v160, v144
	s_waitcnt lgkmcnt(0)
	v_lshlrev_b32_e32 v66, 16, v66
	v_add_f32_e32 v66, v67, v66
	v_cvt_pk_bf16_f32 v66, v66, s0
	ds_write_b16 v130, v66
	ds_read_u16 v66, v84
	v_add_u32_e32 v67, v160, v145
	s_waitcnt lgkmcnt(0)
	v_lshlrev_b32_e32 v66, 16, v66
	v_add_f32_e32 v66, v68, v66
	v_cvt_pk_bf16_f32 v66, v66, s0
	ds_write_b16 v84, v66
	ds_read_u16 v66, v67
	v_add_u32_e32 v68, v160, v146
	s_waitcnt lgkmcnt(0)
	v_lshlrev_b32_e32 v66, 16, v66
	v_add_f32_e32 v66, v69, v66
	v_cvt_pk_bf16_f32 v66, v66, s0
	ds_write_b16 v67, v66
	ds_read_u16 v66, v68
	v_add_u32_e32 v67, v160, v147
	s_waitcnt lgkmcnt(0)
	v_lshlrev_b32_e32 v66, 16, v66
	v_add_f32_e32 v66, v70, v66
	v_cvt_pk_bf16_f32 v66, v66, s0
	ds_write_b16 v68, v66
	ds_read_u16 v66, v67
	v_add_u32_e32 v68, v160, v148
	s_waitcnt lgkmcnt(0)
	v_lshlrev_b32_e32 v66, 16, v66
	v_add_f32_e32 v66, v71, v66
	v_cvt_pk_bf16_f32 v66, v66, s0
	ds_write_b16 v67, v66
	ds_read_u16 v66, v68
	v_add_u32_e32 v67, v160, v149
	s_waitcnt lgkmcnt(0)
	v_lshlrev_b32_e32 v66, 16, v66
	v_add_f32_e32 v66, v72, v66
	v_cvt_pk_bf16_f32 v66, v66, s0
	ds_write_b16 v68, v66
	ds_read_u16 v66, v67
	v_add_u32_e32 v68, v160, v150
	s_waitcnt lgkmcnt(0)
	v_lshlrev_b32_e32 v66, 16, v66
	v_add_f32_e32 v66, v73, v66
	v_cvt_pk_bf16_f32 v66, v66, s0
	ds_write_b16 v67, v66
	ds_read_u16 v66, v68
	v_add_u32_e32 v67, v160, v151
	s_waitcnt lgkmcnt(0)
	v_lshlrev_b32_e32 v66, 16, v66
	v_add_f32_e32 v66, v74, v66
	v_cvt_pk_bf16_f32 v66, v66, s0
	ds_write_b16 v68, v66
	ds_read_u16 v66, v67
	v_add_u32_e32 v68, v160, v152
	s_waitcnt lgkmcnt(0)
	v_lshlrev_b32_e32 v66, 16, v66
	v_add_f32_e32 v66, v75, v66
	v_cvt_pk_bf16_f32 v66, v66, s0
	ds_write_b16 v67, v66
	ds_read_u16 v66, v68
	v_add_u32_e32 v67, v160, v153
	s_waitcnt lgkmcnt(0)
	v_lshlrev_b32_e32 v66, 16, v66
	v_add_f32_e32 v66, v76, v66
	v_cvt_pk_bf16_f32 v66, v66, s0
	ds_write_b16 v68, v66
	ds_read_u16 v66, v67
	v_add_u32_e32 v68, v160, v154
	s_waitcnt lgkmcnt(0)
	v_lshlrev_b32_e32 v66, 16, v66
	v_add_f32_e32 v66, v77, v66
	v_cvt_pk_bf16_f32 v66, v66, s0
	ds_write_b16 v67, v66
	ds_read_u16 v66, v68
	v_add_u32_e32 v67, v160, v155
	s_waitcnt lgkmcnt(0)
	v_lshlrev_b32_e32 v66, 16, v66
	v_add_f32_e32 v66, v78, v66
	v_cvt_pk_bf16_f32 v66, v66, s0
	ds_write_b16 v68, v66
	ds_read_u16 v66, v67
	v_add_u32_e32 v68, v160, v156
	s_waitcnt lgkmcnt(0)
	v_lshlrev_b32_e32 v66, 16, v66
	v_add_f32_e32 v66, v79, v66
	v_cvt_pk_bf16_f32 v66, v66, s0
	ds_write_b16 v67, v66
	ds_read_u16 v66, v68
	s_waitcnt lgkmcnt(0)
	v_lshlrev_b32_e32 v66, 16, v66
	v_add_f32_e32 v66, v80, v66
	v_cvt_pk_bf16_f32 v66, v66, s0
	ds_write_b16 v68, v66
	v_add_u32_e32 v66, v160, v157
	ds_read_u16 v67, v66
	s_waitcnt lgkmcnt(0)
	v_lshlrev_b32_e32 v67, 16, v67
	v_add_f32_e32 v67, v81, v67
	v_cvt_pk_bf16_f32 v67, v67, s0
	ds_write_b16 v66, v67
	ds_read_b128 v[66:69], v137 offset:37984
	ds_read_b128 v[70:73], v137 offset:37952
	ds_read_b128 v[74:77], v137 offset:37920
	ds_read_b128 v[78:81], v137 offset:37888
	ds_read_b128 v[168:171], v132 offset:17408
	s_waitcnt lgkmcnt(4)
	v_pk_mul_f32 v[48:49], v[48:49], v[68:69]
	v_pk_mul_f32 v[46:47], v[46:47], v[66:67]
	ds_read_b128 v[66:69], v133 offset:27648
	s_waitcnt lgkmcnt(4)
	v_pk_mul_f32 v[44:45], v[44:45], v[72:73]
	s_waitcnt lgkmcnt(3)
	v_pk_mul_f32 v[40:41], v[40:41], v[76:77]
	s_waitcnt lgkmcnt(2)
	v_pk_mul_f32 v[36:37], v[36:37], v[80:81]
	v_pk_mul_f32 v[42:43], v[42:43], v[70:71]
	v_pk_mul_f32 v[38:39], v[38:39], v[74:75]
	v_pk_mul_f32 v[34:35], v[34:35], v[78:79]
	ds_read_b128 v[70:73], v132 offset:17440
	ds_read_b128 v[74:77], v133 offset:27680
	s_waitcnt lgkmcnt(2)
	v_mfma_f32_32x32x16_bf16 v[34:49], v[168:171], v[66:69], v[34:49]
	ds_read_b128 v[78:81], v137 offset:38112
	ds_read_b128 v[168:171], v137 offset:38080
	ds_read_b128 v[172:175], v137 offset:38016
	ds_read_b128 v[176:179], v137 offset:38048
	s_movk_i32 s42, 0x1000
	s_waitcnt lgkmcnt(3)
	v_pk_mul_f32 v[64:65], v[64:65], v[80:81]
	s_waitcnt lgkmcnt(2)
	v_pk_mul_f32 v[60:61], v[60:61], v[170:171]
	s_waitcnt lgkmcnt(1)
	v_pk_mul_f32 v[52:53], v[52:53], v[174:175]
	s_waitcnt lgkmcnt(0)
	v_pk_mul_f32 v[56:57], v[56:57], v[178:179]
	v_pk_mul_f32 v[62:63], v[62:63], v[78:79]
	v_mfma_f32_32x32x16_bf16 v[34:49], v[70:73], v[74:77], v[34:49]
	ds_read_b128 v[70:73], v132 offset:19968
	ds_read_b128 v[78:81], v132 offset:20000
	v_mul_f32_e64 v58, v58, v168
	v_mul_f32_e64 v59, v59, v169
	v_mul_f32_e64 v54, v54, v176
	v_mul_f32_e64 v55, v55, v177
	v_pk_mul_f32 v[50:51], v[50:51], v[172:173]
	s_lshl_b32 s52, s97, 1
	s_waitcnt lgkmcnt(1)
	v_mfma_f32_32x32x16_bf16 v[50:65], v[70:73], v[66:69], v[50:65]
	ds_read_b128 v[70:73], v137 offset:38240
	ds_read_b128 v[168:171], v137 offset:38208
	ds_read_b128 v[172:175], v137 offset:38144
	ds_read_b128 v[176:179], v137 offset:38176
	s_waitcnt lgkmcnt(3)
	v_pk_mul_f32 v[32:33], v[32:33], v[72:73]
	s_waitcnt lgkmcnt(2)
	v_pk_mul_f32 v[28:29], v[28:29], v[170:171]
	s_waitcnt lgkmcnt(1)
	v_pk_mul_f32 v[20:21], v[20:21], v[174:175]
	s_waitcnt lgkmcnt(0)
	v_pk_mul_f32 v[24:25], v[24:25], v[178:179]
	v_pk_mul_f32 v[30:31], v[30:31], v[70:71]
	v_mfma_f32_32x32x16_bf16 v[50:65], v[78:81], v[74:77], v[50:65]
	ds_read_b128 v[78:81], v132 offset:22528
	ds_read_b128 v[70:73], v132 offset:22560
	v_mul_f32_e64 v26, v26, v168
	v_mul_f32_e64 v27, v27, v169
	v_mul_f32_e64 v22, v22, v176
	v_mul_f32_e64 v23, v23, v177
	v_pk_mul_f32 v[18:19], v[18:19], v[172:173]
	s_waitcnt lgkmcnt(1)
	s_nop 0
	v_mfma_f32_32x32x16_bf16 v[18:33], v[78:81], v[66:69], v[18:33]
	ds_read_b128 v[78:81], v137 offset:38368
	ds_read_b128 v[168:171], v137 offset:38336
	ds_read_b128 v[172:175], v137 offset:38272
	ds_read_b128 v[176:179], v137 offset:38304
	s_waitcnt lgkmcnt(3)
	v_pk_mul_f32 v[16:17], v[16:17], v[80:81]
	s_waitcnt lgkmcnt(2)
	v_pk_mul_f32 v[12:13], v[12:13], v[170:171]
	s_waitcnt lgkmcnt(1)
	v_pk_mul_f32 v[4:5], v[4:5], v[174:175]
	s_waitcnt lgkmcnt(0)
	v_pk_mul_f32 v[8:9], v[8:9], v[178:179]
	v_pk_mul_f32 v[14:15], v[14:15], v[78:79]
	v_mfma_f32_32x32x16_bf16 v[18:33], v[70:73], v[74:77], v[18:33]
	ds_read_b128 v[70:73], v132 offset:25088
	ds_read_b128 v[78:81], v132 offset:25120
	v_mul_f32_e64 v10, v10, v168
	v_mul_f32_e64 v11, v11, v169
	v_mul_f32_e64 v6, v6, v176
	v_mul_f32_e64 v7, v7, v177
	v_pk_mul_f32 v[2:3], v[2:3], v[172:173]
	s_waitcnt lgkmcnt(0)
	s_barrier
	v_mfma_f32_32x32x16_bf16 v[2:17], v[70:73], v[66:69], v[2:17]
	v_lshl_add_u32 v66, s46, 4, v158
	v_or_b32_e32 v66, s47, v66
	v_ashrrev_i32_e32 v67, 31, v66
	v_lshlrev_b64 v[66:67], 16, v[66:67]
	v_lshl_add_u64 v[66:67], v[94:95], 0, v[66:67]
	global_store_dword v[66:67], v34, off
	global_store_dword v[66:67], v35, off offset:512
	global_store_dword v[66:67], v36, off offset:1024
	global_store_dword v[66:67], v37, off offset:1536
	v_add_co_u32_e32 v34, vcc, s42, v66
	v_mfma_f32_32x32x16_bf16 v[2:17], v[78:81], v[74:77], v[2:17]
	s_nop 0
	v_addc_co_u32_e32 v35, vcc, 0, v67, vcc
	v_add_co_u32_e32 v36, vcc, s78, v66
	v_xor_b32_e32 v80, 1, v163
	s_nop 0
	v_addc_co_u32_e32 v37, vcc, 0, v67, vcc
	global_store_dword v[36:37], v38, off offset:-4096
	global_store_dword v[34:35], v39, off offset:512
	global_store_dword v[34:35], v40, off offset:1024
	global_store_dword v[34:35], v41, off offset:1536
	global_store_dword v[36:37], v42, off
	global_store_dword v[36:37], v43, off offset:512
	global_store_dword v[36:37], v44, off offset:1024
	global_store_dword v[36:37], v45, off offset:1536
	v_add_co_u32_e32 v34, vcc, s79, v66
	s_nop 1
	v_addc_co_u32_e32 v35, vcc, 0, v67, vcc
	v_add_co_u32_e32 v36, vcc, s80, v66
	s_nop 1
	v_addc_co_u32_e32 v37, vcc, 0, v67, vcc
	global_store_dword v[36:37], v46, off offset:-4096
	global_store_dword v[34:35], v47, off offset:512
	global_store_dword v[34:35], v48, off offset:1024
	global_store_dword v[34:35], v49, off offset:1536
	global_store_dword v[36:37], v50, off
	global_store_dword v[36:37], v51, off offset:512
	global_store_dword v[36:37], v52, off offset:1024
	global_store_dword v[36:37], v53, off offset:1536
	v_add_co_u32_e32 v34, vcc, s81, v66
	s_nop 1
	v_addc_co_u32_e32 v35, vcc, 0, v67, vcc
	v_add_co_u32_e32 v36, vcc, s82, v66
	s_nop 1
	v_addc_co_u32_e32 v37, vcc, 0, v67, vcc
	global_store_dword v[36:37], v54, off offset:-4096
	global_store_dword v[34:35], v55, off offset:512
	global_store_dword v[34:35], v56, off offset:1024
	global_store_dword v[34:35], v57, off offset:1536
	global_store_dword v[36:37], v58, off
	global_store_dword v[36:37], v59, off offset:512
	global_store_dword v[36:37], v60, off offset:1024
	global_store_dword v[36:37], v61, off offset:1536
	v_add_co_u32_e32 v34, vcc, s83, v66
	s_nop 1
	v_addc_co_u32_e32 v35, vcc, 0, v67, vcc
	v_add_co_u32_e32 v36, vcc, s84, v66
	s_nop 1
	v_addc_co_u32_e32 v37, vcc, 0, v67, vcc
	global_store_dword v[36:37], v62, off offset:-4096
	global_store_dword v[34:35], v63, off offset:512
	global_store_dword v[34:35], v64, off offset:1024
	global_store_dword v[34:35], v65, off offset:1536
	global_store_dword v[36:37], v18, off
	global_store_dword v[36:37], v19, off offset:512
	global_store_dword v[36:37], v20, off offset:1024
	global_store_dword v[36:37], v21, off offset:1536
	v_add_co_u32_e32 v18, vcc, s85, v66
	s_nop 1
	v_addc_co_u32_e32 v19, vcc, 0, v67, vcc
	v_add_co_u32_e32 v20, vcc, s86, v66
	s_nop 1
	v_addc_co_u32_e32 v21, vcc, 0, v67, vcc
	global_store_dword v[20:21], v22, off offset:-4096
	global_store_dword v[18:19], v23, off offset:512
	global_store_dword v[18:19], v24, off offset:1024
	global_store_dword v[18:19], v25, off offset:1536
	global_store_dword v[20:21], v26, off
	global_store_dword v[20:21], v27, off offset:512
	global_store_dword v[20:21], v28, off offset:1024
	global_store_dword v[20:21], v29, off offset:1536
	v_add_co_u32_e32 v18, vcc, s87, v66
	v_lshl_add_u64 v[28:29], v[98:99], 0, s[52:53]
	s_nop 0
	v_addc_co_u32_e32 v19, vcc, 0, v67, vcc
	v_add_co_u32_e32 v20, vcc, s88, v66
	v_xor_b32_e32 v26, 8, v163
	s_nop 0
	v_addc_co_u32_e32 v21, vcc, 0, v67, vcc
	global_store_dword v[20:21], v30, off offset:-4096
	global_store_dword v[18:19], v31, off offset:512
	global_store_dword v[18:19], v32, off offset:1024
	global_store_dword v[18:19], v33, off offset:1536
	global_store_dword v[20:21], v2, off
	global_store_dword v[20:21], v3, off offset:512
	global_store_dword v[20:21], v4, off offset:1024
	global_store_dword v[20:21], v5, off offset:1536
	v_add_co_u32_e32 v2, vcc, s89, v66
	v_or_b32_e32 v30, s58, v159
	s_nop 0
	v_addc_co_u32_e32 v3, vcc, 0, v67, vcc
	v_add_co_u32_e32 v4, vcc, s90, v66
	v_ashrrev_i32_e32 v31, 31, v30
	s_nop 0
	v_addc_co_u32_e32 v5, vcc, 0, v67, vcc
	global_store_dword v[4:5], v6, off offset:-4096
	global_store_dword v[2:3], v7, off offset:512
	global_store_dword v[2:3], v8, off offset:1024
	global_store_dword v[2:3], v9, off offset:1536
	global_store_dword v[4:5], v10, off
	global_store_dword v[4:5], v11, off offset:512
	global_store_dword v[4:5], v12, off offset:1024
	global_store_dword v[4:5], v13, off offset:1536
	v_add_co_u32_e32 v2, vcc, s91, v66
	v_lshlrev_b64 v[10:11], 11, v[30:31]
	s_nop 0
	v_addc_co_u32_e32 v3, vcc, 0, v67, vcc
	v_lshl_add_u64 v[32:33], v[28:29], 0, v[10:11]
	global_store_dword v[2:3], v14, off
	global_store_dword v[2:3], v15, off offset:512
	global_store_dword v[2:3], v16, off offset:1024
	global_store_dword v[2:3], v17, off offset:1536
	s_waitcnt vmcnt(63) expcnt(7) lgkmcnt(15)
	s_barrier
	global_load_dwordx4 v[2:5], v[96:97], off offset:16
	global_load_dwordx4 v[6:9], v[96:97], off
	global_load_dwordx4 v[44:47], v[32:33], off
	v_add_co_u32_e32 v38, vcc, s92, v32
	ds_read_b128 v[48:51], v162
	ds_read_b128 v[52:55], v162 offset:8704
	v_addc_co_u32_e32 v39, vcc, 0, v33, vcc
	global_load_dwordx4 v[56:59], v[38:39], off
	v_add_co_u32_e32 v34, vcc, s93, v32
	v_or_b32_e32 v10, 64, v30
	s_nop 0
	v_addc_co_u32_e32 v35, vcc, 0, v33, vcc
	v_cmp_lt_i32_e32 vcc, v26, v166
	s_waitcnt lgkmcnt(1)
	v_and_b32_e32 v67, 0xffff0000, v48
	s_waitcnt lgkmcnt(0)
	v_and_b32_e32 v77, 0xffff0000, v52
	v_cndmask_b32_e32 v26, v163, v26, vcc
	v_lshlrev_b32_e32 v41, 2, v26
	v_xor_b32_e32 v26, 4, v163
	v_ashrrev_i32_e32 v11, 31, v10
	v_cmp_lt_i32_e32 vcc, v26, v166
	v_lshlrev_b32_e32 v60, 16, v51
	v_and_b32_e32 v61, 0xffff0000, v51
	v_lshlrev_b32_e32 v62, 16, v50
	v_and_b32_e32 v63, 0xffff0000, v50
	v_lshlrev_b32_e32 v50, 16, v49
	v_and_b32_e32 v51, 0xffff0000, v49
	v_lshlrev_b32_e32 v66, 16, v48
	v_lshlrev_b32_e32 v72, 16, v53
	v_and_b32_e32 v73, 0xffff0000, v53
	v_lshlrev_b32_e32 v76, 16, v52
	v_mov_b32_e32 v78, v77
	v_mov_b32_e32 v79, v67
	v_lshlrev_b64 v[10:11], 11, v[10:11]
	v_cndmask_b32_e32 v26, v163, v26, vcc
	v_pk_mul_f32 v[64:65], v[50:51], v[50:51]
	v_pk_mul_f32 v[74:75], v[72:73], v[72:73]
	v_mov_b32_e32 v52, v76
	v_mov_b32_e32 v53, v66
	v_pk_mul_f32 v[78:79], v[78:79], v[78:79]
	v_lshl_add_u64 v[36:37], v[28:29], 0, v[10:11]
	v_lshlrev_b32_e32 v40, 2, v26
	v_xor_b32_e32 v26, 2, v163
	v_lshlrev_b32_e32 v70, 16, v54
	v_and_b32_e32 v71, 0xffff0000, v54
	v_pk_fma_f32 v[52:53], v[52:53], v[52:53], v[78:79]
	v_mov_b32_e32 v78, v74
	v_mov_b32_e32 v79, v64
	ds_read_b128 v[22:25], v162 offset:17408
	ds_read_b128 v[18:21], v162 offset:26112
	global_load_dwordx4 v[14:17], v[36:37], off
	global_load_dwordx4 v[10:13], v[34:35], off
	v_cmp_lt_i32_e32 vcc, v26, v166
	v_pk_mul_f32 v[42:43], v[62:63], v[62:63]
	v_lshlrev_b32_e32 v48, 16, v55
	v_and_b32_e32 v49, 0xffff0000, v55
	v_pk_mul_f32 v[54:55], v[70:71], v[70:71]
	v_pk_add_f32 v[52:53], v[78:79], v[52:53]
	v_mov_b32_e32 v64, v75
	v_cndmask_b32_e32 v26, v163, v26, vcc
	v_pk_add_f32 v[52:53], v[64:65], v[52:53]
	v_mov_b32_e32 v64, v54
	v_mov_b32_e32 v65, v42
	v_lshlrev_b32_e32 v31, 2, v26
	v_pk_mul_f32 v[26:27], v[60:61], v[60:61]
	v_pk_mul_f32 v[68:69], v[48:49], v[48:49]
	v_pk_add_f32 v[52:53], v[64:65], v[52:53]
	v_mov_b32_e32 v42, v55
	v_pk_add_f32 v[42:43], v[42:43], v[52:53]
	v_mov_b32_e32 v52, v68
	v_mov_b32_e32 v53, v26
	v_pk_add_f32 v[42:43], v[52:53], v[42:43]
	v_mov_b32_e32 v26, v69
	v_pk_add_f32 v[26:27], v[26:27], v[42:43]
	ds_bpermute_b32 v53, v41, v27
	ds_bpermute_b32 v52, v41, v26
	v_cmp_lt_i32_e32 vcc, v80, v166
	s_waitcnt lgkmcnt(0)
	v_pk_add_f32 v[26:27], v[26:27], v[52:53]
	ds_bpermute_b32 v53, v40, v27
	ds_bpermute_b32 v52, v40, v26
	v_cndmask_b32_e32 v42, v163, v80, vcc
	v_lshlrev_b32_e32 v42, 2, v42
	s_waitcnt vmcnt(3)
	v_lshlrev_b32_e32 v54, 16, v47
	v_and_b32_e32 v55, 0xffff0000, v47
	s_waitcnt lgkmcnt(0)
	v_pk_add_f32 v[26:27], v[26:27], v[52:53]
	ds_bpermute_b32 v53, v31, v27
	ds_bpermute_b32 v52, v31, v26
	v_lshlrev_b32_e32 v64, 16, v46
	v_and_b32_e32 v65, 0xffff0000, v46
	v_lshlrev_b32_e32 v46, 16, v45
	v_and_b32_e32 v47, 0xffff0000, v45
	s_waitcnt lgkmcnt(0)
	v_pk_add_f32 v[26:27], v[26:27], v[52:53]
	v_lshlrev_b32_e32 v68, 16, v44
	v_and_b32_e32 v69, 0xffff0000, v44
	ds_bpermute_b32 v45, v42, v27
	ds_bpermute_b32 v44, v42, v26
	s_waitcnt vmcnt(2)
	v_lshlrev_b32_e32 v74, 16, v59
	v_and_b32_e32 v75, 0xffff0000, v59
	v_lshlrev_b32_e32 v52, 16, v58
	v_and_b32_e32 v53, 0xffff0000, v58
	s_waitcnt lgkmcnt(0)
	v_pk_add_f32 v[44:45], v[26:27], v[44:45]
	v_mov_b64_e32 v[26:27], s[56:57]
	v_pk_fma_f32 v[78:79], v[44:45], s[54:55], v[26:27] op_sel_hi:[1,0,0]
	v_lshlrev_b32_e32 v58, 16, v57
	v_mul_f32_e32 v43, 0x4b800000, v79
	v_cmp_gt_f32_e32 vcc, s94, v79
	v_and_b32_e32 v59, 0xffff0000, v57
	v_lshlrev_b32_e32 v80, 16, v56
	v_cndmask_b32_e32 v43, v79, v43, vcc
	v_rsq_f32_e32 v43, v43
	v_and_b32_e32 v81, 0xffff0000, v56
	v_mul_f32_e32 v44, 0x45800000, v43
	v_cndmask_b32_e32 v44, v43, v44, vcc
	v_pk_mul_f32 v[50:51], v[44:45], v[50:51] op_sel_hi:[0,1]
	v_mul_f32_e32 v43, 0x4b800000, v78
	v_cmp_gt_f32_e32 vcc, s94, v78
	v_pk_mul_f32 v[50:51], v[8:9], v[50:51]
	v_pk_mul_f32 v[56:57], v[44:45], v[66:67] op_sel_hi:[0,1]
	v_cndmask_b32_e32 v43, v78, v43, vcc
	v_pk_mul_f32 v[46:47], v[50:51], v[46:47]
	v_pk_mul_f32 v[50:51], v[44:45], v[62:63] op_sel_hi:[0,1]
	v_pk_mul_f32 v[44:45], v[44:45], v[60:61] op_sel_hi:[0,1]
	v_rsq_f32_e32 v43, v43
	v_pk_mul_f32 v[56:57], v[6:7], v[56:57]
	v_pk_mul_f32 v[50:51], v[2:3], v[50:51]
	v_pk_mul_f32 v[44:45], v[4:5], v[44:45]
	v_pk_mul_f32 v[56:57], v[56:57], v[68:69]
	v_pk_mul_f32 v[50:51], v[50:51], v[64:65]
	v_pk_mul_f32 v[54:55], v[44:45], v[54:55]
	v_cvt_pk_bf16_f32 v44, v56, v57
	v_cvt_pk_bf16_f32 v45, v46, v47
	v_cvt_pk_bf16_f32 v46, v50, v51
	v_cvt_pk_bf16_f32 v47, v54, v55
	global_store_dwordx4 v[32:33], v[44:47], off
	v_and_b32_e32 v61, 0xffff0000, v22
	v_lshlrev_b32_e32 v56, 16, v23
	v_mul_f32_e32 v44, 0x45800000, v43
	v_cndmask_b32_e32 v44, v43, v44, vcc
	v_pk_mul_f32 v[50:51], v[44:45], v[72:73] op_sel_hi:[0,1]
	v_pk_mul_f32 v[54:55], v[44:45], v[70:71] op_sel_hi:[0,1]
	v_and_b32_e32 v71, 0xffff0000, v18
	v_pk_mul_f32 v[50:51], v[8:9], v[50:51]
	v_and_b32_e32 v57, 0xffff0000, v23
	v_lshlrev_b32_e32 v60, 16, v22
	v_lshlrev_b32_e32 v66, 16, v19
	v_and_b32_e32 v67, 0xffff0000, v19
	v_lshlrev_b32_e32 v70, 16, v18
	v_mov_b32_e32 v72, v71
	v_mov_b32_e32 v73, v61
	v_pk_mul_f32 v[46:47], v[44:45], v[76:77] op_sel_hi:[0,1]
	v_pk_mul_f32 v[50:51], v[50:51], v[58:59]
	v_pk_mul_f32 v[54:55], v[2:3], v[54:55]
	v_pk_mul_f32 v[44:45], v[44:45], v[48:49] op_sel_hi:[0,1]
	v_pk_mul_f32 v[58:59], v[56:57], v[56:57]
	v_pk_mul_f32 v[68:69], v[66:67], v[66:67]
	v_mov_b32_e32 v18, v70
	v_mov_b32_e32 v19, v60
	v_pk_mul_f32 v[72:73], v[72:73], v[72:73]
	v_pk_mul_f32 v[52:53], v[54:55], v[52:53]
	v_pk_mul_f32 v[44:45], v[4:5], v[44:45]
	v_lshlrev_b32_e32 v54, 16, v24
	v_and_b32_e32 v55, 0xffff0000, v24
	v_lshlrev_b32_e32 v64, 16, v20
	v_and_b32_e32 v65, 0xffff0000, v20
	v_pk_fma_f32 v[18:19], v[18:19], v[18:19], v[72:73]
	v_mov_b32_e32 v72, v68
	v_mov_b32_e32 v73, v58
	v_pk_mul_f32 v[46:47], v[6:7], v[46:47]
	v_pk_mul_f32 v[48:49], v[44:45], v[74:75]
	v_cvt_pk_bf16_f32 v45, v50, v51
	v_lshlrev_b32_e32 v50, 16, v25
	v_and_b32_e32 v51, 0xffff0000, v25
	v_pk_mul_f32 v[24:25], v[54:55], v[54:55]
	v_lshlrev_b32_e32 v62, 16, v21
	v_and_b32_e32 v63, 0xffff0000, v21
	v_pk_mul_f32 v[20:21], v[64:65], v[64:65]
	v_pk_add_f32 v[18:19], v[72:73], v[18:19]
	v_mov_b32_e32 v58, v69
	v_pk_mul_f32 v[46:47], v[46:47], v[80:81]
	v_pk_add_f32 v[18:19], v[58:59], v[18:19]
	v_mov_b32_e32 v58, v20
	v_mov_b32_e32 v59, v24
	v_cvt_pk_bf16_f32 v44, v46, v47
	v_pk_mul_f32 v[46:47], v[50:51], v[50:51]
	v_pk_mul_f32 v[22:23], v[62:63], v[62:63]
	v_pk_add_f32 v[18:19], v[58:59], v[18:19]
	v_mov_b32_e32 v24, v21
	v_pk_add_f32 v[18:19], v[24:25], v[18:19]
	v_mov_b32_e32 v20, v22
	v_mov_b32_e32 v21, v46
	v_pk_add_f32 v[18:19], v[20:21], v[18:19]
	v_mov_b32_e32 v46, v23
	v_pk_add_f32 v[18:19], v[46:47], v[18:19]
	ds_bpermute_b32 v21, v41, v19
	ds_bpermute_b32 v20, v41, v18
	v_cvt_pk_bf16_f32 v46, v52, v53
	v_cvt_pk_bf16_f32 v47, v48, v49
	global_store_dwordx4 v[38:39], v[44:47], off
	s_waitcnt vmcnt(3)
	v_lshlrev_b32_e32 v22, 16, v17
	s_waitcnt lgkmcnt(0)
	v_pk_add_f32 v[18:19], v[18:19], v[20:21]
	ds_bpermute_b32 v21, v40, v19
	ds_bpermute_b32 v20, v40, v18
	v_and_b32_e32 v23, 0xffff0000, v17
	v_lshlrev_b32_e32 v24, 16, v16
	v_and_b32_e32 v25, 0xffff0000, v16
	v_lshlrev_b32_e32 v16, 16, v15
	s_waitcnt lgkmcnt(0)
	v_pk_add_f32 v[18:19], v[18:19], v[20:21]
	ds_bpermute_b32 v21, v31, v19
	ds_bpermute_b32 v20, v31, v18
	v_and_b32_e32 v17, 0xffff0000, v15
	v_lshlrev_b32_e32 v38, 16, v14
	v_and_b32_e32 v39, 0xffff0000, v14
	s_waitcnt vmcnt(2)
	v_lshlrev_b32_e32 v14, 16, v13
	s_waitcnt lgkmcnt(0)
	v_pk_add_f32 v[18:19], v[18:19], v[20:21]
	ds_bpermute_b32 v21, v42, v19
	ds_bpermute_b32 v20, v42, v18
	v_and_b32_e32 v15, 0xffff0000, v13
	v_lshlrev_b32_e32 v44, 16, v12
	v_and_b32_e32 v45, 0xffff0000, v12
	v_lshlrev_b32_e32 v46, 16, v11
	s_waitcnt lgkmcnt(0)
	v_pk_add_f32 v[12:13], v[18:19], v[20:21]
	v_and_b32_e32 v19, 0xffff0000, v10
	v_pk_fma_f32 v[12:13], v[12:13], s[54:55], v[26:27] op_sel_hi:[1,0,0]
	v_and_b32_e32 v47, 0xffff0000, v11
	v_mul_f32_e32 v18, 0x4b800000, v13
	v_cmp_gt_f32_e32 vcc, s94, v13
	s_nop 1
	v_cndmask_b32_e32 v13, v13, v18, vcc
	v_rsq_f32_e32 v13, v13
	v_lshlrev_b32_e32 v18, 16, v10
	v_mul_f32_e32 v10, 0x45800000, v13
	v_cndmask_b32_e32 v10, v13, v10, vcc
	v_pk_mul_f32 v[20:21], v[10:11], v[60:61] op_sel_hi:[0,1]
	v_pk_mul_f32 v[20:21], v[6:7], v[20:21]
	v_mul_f32_e32 v13, 0x4b800000, v12
	v_pk_mul_f32 v[20:21], v[20:21], v[38:39]
	v_pk_mul_f32 v[38:39], v[10:11], v[56:57] op_sel_hi:[0,1]
	v_pk_mul_f32 v[38:39], v[8:9], v[38:39]
	v_cmp_gt_f32_e32 vcc, s94, v12
	v_pk_mul_f32 v[16:17], v[38:39], v[16:17]
	v_pk_mul_f32 v[38:39], v[10:11], v[54:55] op_sel_hi:[0,1]
	v_pk_mul_f32 v[10:11], v[10:11], v[50:51] op_sel_hi:[0,1]
	v_pk_mul_f32 v[10:11], v[4:5], v[10:11]
	v_cndmask_b32_e32 v12, v12, v13, vcc
	v_pk_mul_f32 v[22:23], v[10:11], v[22:23]
	v_cvt_pk_bf16_f32 v11, v16, v17
	v_rsq_f32_e32 v16, v12
	v_pk_mul_f32 v[38:39], v[2:3], v[38:39]
	v_cvt_pk_bf16_f32 v10, v20, v21
	v_pk_mul_f32 v[24:25], v[38:39], v[24:25]
	v_cvt_pk_bf16_f32 v13, v22, v23
	v_cvt_pk_bf16_f32 v12, v24, v25
	global_store_dwordx4 v[36:37], v[10:13], off
	s_nop 1
	v_mul_f32_e32 v10, 0x45800000, v16
	v_cndmask_b32_e32 v10, v16, v10, vcc
	v_or_b32_e32 v16, 0x80, v30
	v_ashrrev_i32_e32 v17, 31, v16
	v_lshlrev_b64 v[16:17], 11, v[16:17]
	v_lshl_add_u64 v[24:25], v[28:29], 0, v[16:17]
	global_load_dwordx4 v[20:23], v[24:25], off
	v_pk_mul_f32 v[12:13], v[10:11], v[70:71] op_sel_hi:[0,1]
	v_pk_mul_f32 v[16:17], v[10:11], v[66:67] op_sel_hi:[0,1]
	v_pk_mul_f32 v[12:13], v[6:7], v[12:13]
	v_pk_mul_f32 v[16:17], v[8:9], v[16:17]
	v_pk_mul_f32 v[12:13], v[12:13], v[18:19]
	v_pk_mul_f32 v[18:19], v[16:17], v[46:47]
	v_pk_mul_f32 v[16:17], v[10:11], v[64:65] op_sel_hi:[0,1]
	v_pk_mul_f32 v[16:17], v[2:3], v[16:17]
	v_pk_mul_f32 v[10:11], v[10:11], v[62:63] op_sel_hi:[0,1]
	v_pk_mul_f32 v[44:45], v[16:17], v[44:45]
	v_add_co_u32_e32 v16, vcc, s95, v32
	v_pk_mul_f32 v[10:11], v[4:5], v[10:11]
	s_nop 0
	v_addc_co_u32_e32 v17, vcc, 0, v33, vcc
	global_load_dwordx4 v[36:39], v[16:17], off
	v_pk_mul_f32 v[14:15], v[10:11], v[14:15]
	v_cvt_pk_bf16_f32 v10, v12, v13
	v_cvt_pk_bf16_f32 v11, v18, v19
	v_cvt_pk_bf16_f32 v12, v44, v45
	v_cvt_pk_bf16_f32 v13, v14, v15
	global_store_dwordx4 v[34:35], v[10:13], off
	ds_read_b128 v[32:35], v162 offset:34816
	ds_read_b128 v[44:47], v162 offset:43520
	v_or_b32_e32 v10, 0xc0, v30
	v_ashrrev_i32_e32 v11, 31, v10
	v_add_u32_e32 v18, 0xe0, v30
	s_waitcnt lgkmcnt(1)
	v_and_b32_e32 v63, 0xffff0000, v32
	s_waitcnt lgkmcnt(0)
	v_and_b32_e32 v73, 0xffff0000, v44
	v_lshlrev_b32_e32 v58, 16, v33
	v_and_b32_e32 v59, 0xffff0000, v33
	v_lshlrev_b32_e32 v62, 16, v32
	v_lshlrev_b32_e32 v68, 16, v45
	v_and_b32_e32 v69, 0xffff0000, v45
	v_lshlrev_b32_e32 v72, 16, v44
	v_mov_b32_e32 v74, v73
	v_mov_b32_e32 v75, v63
	v_pk_mul_f32 v[60:61], v[58:59], v[58:59]
	v_pk_mul_f32 v[70:71], v[68:69], v[68:69]
	v_mov_b32_e32 v44, v72
	v_mov_b32_e32 v45, v62
	v_pk_mul_f32 v[74:75], v[74:75], v[74:75]
	v_lshlrev_b32_e32 v56, 16, v34
	v_and_b32_e32 v57, 0xffff0000, v34
	v_lshlrev_b32_e32 v66, 16, v46
	v_and_b32_e32 v67, 0xffff0000, v46
	v_pk_fma_f32 v[44:45], v[44:45], v[44:45], v[74:75]
	v_mov_b32_e32 v74, v70
	v_mov_b32_e32 v75, v60
	v_lshlrev_b32_e32 v52, 16, v35
	v_and_b32_e32 v53, 0xffff0000, v35
	v_pk_mul_f32 v[34:35], v[56:57], v[56:57]
	v_lshlrev_b32_e32 v64, 16, v47
	v_and_b32_e32 v65, 0xffff0000, v47
	v_pk_mul_f32 v[46:47], v[66:67], v[66:67]
	v_pk_add_f32 v[44:45], v[74:75], v[44:45]
	v_mov_b32_e32 v60, v71
	v_pk_add_f32 v[44:45], v[60:61], v[44:45]
	v_mov_b32_e32 v60, v46
	v_mov_b32_e32 v61, v34
	v_pk_mul_f32 v[54:55], v[52:53], v[52:53]
	v_pk_mul_f32 v[32:33], v[64:65], v[64:65]
	v_pk_add_f32 v[44:45], v[60:61], v[44:45]
	v_mov_b32_e32 v34, v47
	v_pk_add_f32 v[34:35], v[34:35], v[44:45]
	v_mov_b32_e32 v44, v32
	v_mov_b32_e32 v45, v54
	v_pk_add_f32 v[34:35], v[44:45], v[34:35]
	v_mov_b32_e32 v54, v33
	v_pk_add_f32 v[54:55], v[54:55], v[34:35]
	ds_bpermute_b32 v61, v41, v55
	ds_bpermute_b32 v60, v41, v54
	v_lshlrev_b64 v[10:11], 11, v[10:11]
	v_ashrrev_i32_e32 v19, 31, v18
	v_lshl_add_u64 v[14:15], v[28:29], 0, v[10:11]
	v_lshlrev_b64 v[18:19], 11, v[18:19]
	s_waitcnt lgkmcnt(0)
	v_pk_add_f32 v[54:55], v[54:55], v[60:61]
	ds_bpermute_b32 v61, v40, v55
	ds_bpermute_b32 v60, v40, v54
	ds_read_b128 v[48:51], v162 offset:52224
	ds_read_b128 v[10:13], v162 offset:60928
	v_lshl_add_u64 v[18:19], v[28:29], 0, v[18:19]
	global_load_dwordx4 v[32:35], v[14:15], off
	global_load_dwordx4 v[44:47], v[18:19], off
	s_waitcnt vmcnt(4)
	v_lshlrev_b32_e32 v28, 16, v23
	s_waitcnt lgkmcnt(2)
	v_pk_add_f32 v[54:55], v[54:55], v[60:61]
	ds_bpermute_b32 v61, v31, v55
	ds_bpermute_b32 v60, v31, v54
	v_and_b32_e32 v29, 0xffff0000, v23
	v_lshlrev_b32_e32 v70, 16, v22
	v_and_b32_e32 v71, 0xffff0000, v22
	v_lshlrev_b32_e32 v22, 16, v21
	v_and_b32_e32 v23, 0xffff0000, v21
	v_lshlrev_b32_e32 v74, 16, v20
	v_and_b32_e32 v75, 0xffff0000, v20
	s_waitcnt lgkmcnt(0)
	v_pk_add_f32 v[20:21], v[54:55], v[60:61]
	ds_bpermute_b32 v55, v42, v21
	ds_bpermute_b32 v54, v42, v20
	s_waitcnt vmcnt(3)
	v_lshlrev_b32_e32 v76, 16, v39
	v_and_b32_e32 v77, 0xffff0000, v39
	v_lshlrev_b32_e32 v60, 16, v38
	v_and_b32_e32 v61, 0xffff0000, v38
	s_waitcnt lgkmcnt(0)
	v_pk_add_f32 v[20:21], v[20:21], v[54:55]
	v_lshlrev_b32_e32 v38, 16, v37
	v_pk_fma_f32 v[54:55], v[20:21], s[54:55], v[26:27] op_sel_hi:[1,0,0]
	v_and_b32_e32 v39, 0xffff0000, v37
	v_mul_f32_e32 v20, 0x4b800000, v55
	v_cmp_gt_f32_e32 vcc, s94, v55
	v_lshlrev_b32_e32 v78, 16, v36
	v_and_b32_e32 v79, 0xffff0000, v36
	v_cndmask_b32_e32 v20, v55, v20, vcc
	v_rsq_f32_e32 v20, v20
	s_nop 0
	v_mul_f32_e32 v21, 0x45800000, v20
	v_cndmask_b32_e32 v20, v20, v21, vcc
	v_pk_mul_f32 v[58:59], v[20:21], v[58:59] op_sel_hi:[0,1]
	v_pk_mul_f32 v[36:37], v[20:21], v[62:63] op_sel_hi:[0,1]
	v_pk_mul_f32 v[58:59], v[8:9], v[58:59]
	v_pk_mul_f32 v[56:57], v[20:21], v[56:57] op_sel_hi:[0,1]
	v_pk_mul_f32 v[20:21], v[20:21], v[52:53] op_sel_hi:[0,1]
	v_pk_mul_f32 v[22:23], v[58:59], v[22:23]
	v_pk_mul_f32 v[20:21], v[4:5], v[20:21]
	v_cmp_gt_f32_e32 vcc, s94, v54
	v_pk_mul_f32 v[28:29], v[20:21], v[28:29]
	v_cvt_pk_bf16_f32 v21, v22, v23
	v_mul_f32_e32 v22, 0x4b800000, v54
	v_cndmask_b32_e32 v22, v54, v22, vcc
	v_rsq_f32_e32 v30, v22
	v_pk_mul_f32 v[36:37], v[6:7], v[36:37]
	v_pk_mul_f32 v[56:57], v[2:3], v[56:57]
	v_pk_mul_f32 v[36:37], v[36:37], v[74:75]
	v_pk_mul_f32 v[56:57], v[56:57], v[70:71]
	v_cvt_pk_bf16_f32 v20, v36, v37
	v_cvt_pk_bf16_f32 v22, v56, v57
	v_cvt_pk_bf16_f32 v23, v28, v29
	global_store_dwordx4 v[24:25], v[20:23], off
	v_and_b32_e32 v57, 0xffff0000, v48
	v_lshlrev_b32_e32 v52, 16, v49
	v_mul_f32_e32 v20, 0x45800000, v30
	v_cndmask_b32_e32 v20, v30, v20, vcc
	v_pk_mul_f32 v[28:29], v[20:21], v[66:67] op_sel_hi:[0,1]
	v_and_b32_e32 v67, 0xffff0000, v10
	v_pk_mul_f32 v[24:25], v[20:21], v[68:69] op_sel_hi:[0,1]
	v_and_b32_e32 v53, 0xffff0000, v49
	v_lshlrev_b32_e32 v56, 16, v48
	v_lshlrev_b32_e32 v62, 16, v11
	v_and_b32_e32 v63, 0xffff0000, v11
	v_lshlrev_b32_e32 v66, 16, v10
	v_mov_b32_e32 v68, v67
	v_mov_b32_e32 v69, v57
	v_pk_mul_f32 v[22:23], v[20:21], v[72:73] op_sel_hi:[0,1]
	v_pk_mul_f32 v[24:25], v[8:9], v[24:25]
	v_pk_mul_f32 v[28:29], v[2:3], v[28:29]
	v_pk_mul_f32 v[20:21], v[20:21], v[64:65] op_sel_hi:[0,1]
	v_pk_mul_f32 v[54:55], v[52:53], v[52:53]
	v_pk_mul_f32 v[64:65], v[62:63], v[62:63]
	v_mov_b32_e32 v10, v66
	v_mov_b32_e32 v11, v56
	v_pk_mul_f32 v[68:69], v[68:69], v[68:69]
	v_pk_mul_f32 v[24:25], v[24:25], v[38:39]
	v_pk_mul_f32 v[28:29], v[28:29], v[60:61]
	v_pk_mul_f32 v[20:21], v[4:5], v[20:21]
	v_lshlrev_b32_e32 v38, 16, v50
	v_and_b32_e32 v39, 0xffff0000, v50
	v_lshlrev_b32_e32 v60, 16, v12
	v_and_b32_e32 v61, 0xffff0000, v12
	v_pk_fma_f32 v[10:11], v[10:11], v[10:11], v[68:69]
	v_mov_b32_e32 v68, v64
	v_mov_b32_e32 v69, v54
	v_pk_mul_f32 v[22:23], v[6:7], v[22:23]
	v_pk_mul_f32 v[36:37], v[20:21], v[76:77]
	v_cvt_pk_bf16_f32 v21, v24, v25
	v_lshlrev_b32_e32 v24, 16, v51
	v_and_b32_e32 v25, 0xffff0000, v51
	v_pk_mul_f32 v[50:51], v[38:39], v[38:39]
	v_lshlrev_b32_e32 v48, 16, v13
	v_and_b32_e32 v49, 0xffff0000, v13
	v_pk_mul_f32 v[12:13], v[60:61], v[60:61]
	v_pk_add_f32 v[10:11], v[68:69], v[10:11]
	v_mov_b32_e32 v54, v65
	v_pk_mul_f32 v[22:23], v[22:23], v[78:79]
	v_pk_add_f32 v[10:11], v[54:55], v[10:11]
	v_mov_b32_e32 v54, v12
	v_mov_b32_e32 v55, v50
	v_cvt_pk_bf16_f32 v20, v22, v23
	v_pk_mul_f32 v[22:23], v[24:25], v[24:25]
	v_pk_mul_f32 v[58:59], v[48:49], v[48:49]
	v_pk_add_f32 v[10:11], v[54:55], v[10:11]
	v_mov_b32_e32 v50, v13
	v_pk_add_f32 v[10:11], v[50:51], v[10:11]
	v_mov_b32_e32 v12, v58
	v_mov_b32_e32 v13, v22
	v_pk_add_f32 v[10:11], v[12:13], v[10:11]
	v_mov_b32_e32 v22, v59
	v_pk_add_f32 v[10:11], v[22:23], v[10:11]
	ds_bpermute_b32 v13, v41, v11
	ds_bpermute_b32 v12, v41, v10
	v_cvt_pk_bf16_f32 v23, v36, v37
	v_cvt_pk_bf16_f32 v22, v28, v29
	s_waitcnt vmcnt(2)
	v_lshlrev_b32_e32 v28, 16, v32
	v_and_b32_e32 v29, 0xffff0000, v32
	s_waitcnt lgkmcnt(0)
	v_pk_add_f32 v[10:11], v[10:11], v[12:13]
	ds_bpermute_b32 v13, v40, v11
	ds_bpermute_b32 v12, v40, v10
	global_store_dwordx4 v[16:17], v[20:23], off
	v_lshlrev_b32_e32 v16, 16, v35
	v_and_b32_e32 v17, 0xffff0000, v35
	v_lshlrev_b32_e32 v22, 16, v33
	s_waitcnt lgkmcnt(0)
	v_pk_add_f32 v[10:11], v[10:11], v[12:13]
	ds_bpermute_b32 v13, v31, v11
	ds_bpermute_b32 v12, v31, v10
	v_and_b32_e32 v23, 0xffff0000, v33
	v_lshlrev_b32_e32 v20, 16, v34
	v_and_b32_e32 v21, 0xffff0000, v34
	s_waitcnt vmcnt(2)
	v_lshlrev_b32_e32 v32, 16, v46
	s_waitcnt lgkmcnt(0)
	v_pk_add_f32 v[10:11], v[10:11], v[12:13]
	ds_bpermute_b32 v13, v42, v11
	ds_bpermute_b32 v12, v42, v10
	v_and_b32_e32 v33, 0xffff0000, v46
	v_lshlrev_b32_e32 v30, 16, v47
	v_and_b32_e32 v31, 0xffff0000, v47
	v_lshlrev_b32_e32 v34, 16, v45
	s_waitcnt lgkmcnt(0)
	v_pk_add_f32 v[10:11], v[10:11], v[12:13]
	v_and_b32_e32 v35, 0xffff0000, v45
	v_pk_fma_f32 v[12:13], v[10:11], s[54:55], v[26:27] op_sel_hi:[1,0,0]
	v_lshlrev_b32_e32 v26, 16, v44
	v_mul_f32_e32 v10, 0x4b800000, v13
	v_cmp_gt_f32_e32 vcc, s94, v13
	v_and_b32_e32 v27, 0xffff0000, v44
	s_nop 0
	v_cndmask_b32_e32 v10, v13, v10, vcc
	v_rsq_f32_e32 v10, v10
	v_mul_f32_e32 v13, 0x4b800000, v12
	v_mul_f32_e32 v11, 0x45800000, v10
	v_cndmask_b32_e32 v10, v10, v11, vcc
	v_pk_mul_f32 v[36:37], v[10:11], v[56:57] op_sel_hi:[0,1]
	v_pk_mul_f32 v[36:37], v[6:7], v[36:37]
	v_cmp_gt_f32_e32 vcc, s94, v12
	v_pk_mul_f32 v[28:29], v[36:37], v[28:29]
	v_pk_mul_f32 v[36:37], v[10:11], v[52:53] op_sel_hi:[0,1]
	v_pk_mul_f32 v[36:37], v[8:9], v[36:37]
	v_cndmask_b32_e32 v12, v12, v13, vcc
	v_pk_mul_f32 v[22:23], v[36:37], v[22:23]
	v_pk_mul_f32 v[36:37], v[10:11], v[38:39] op_sel_hi:[0,1]
	v_pk_mul_f32 v[10:11], v[10:11], v[24:25] op_sel_hi:[0,1]
	v_pk_mul_f32 v[10:11], v[4:5], v[10:11]
	v_pk_mul_f32 v[36:37], v[2:3], v[36:37]
	v_pk_mul_f32 v[16:17], v[10:11], v[16:17]
	v_cvt_pk_bf16_f32 v11, v22, v23
	v_rsq_f32_e32 v22, v12
	v_pk_mul_f32 v[20:21], v[36:37], v[20:21]
	v_cvt_pk_bf16_f32 v10, v28, v29
	v_cvt_pk_bf16_f32 v12, v20, v21
	v_cvt_pk_bf16_f32 v13, v16, v17
	global_store_dwordx4 v[14:15], v[10:13], off
	s_nop 1
	v_mul_f32_e32 v10, 0x45800000, v22
	v_cndmask_b32_e32 v10, v22, v10, vcc
	v_pk_mul_f32 v[12:13], v[10:11], v[66:67] op_sel_hi:[0,1]
	v_pk_mul_f32 v[6:7], v[6:7], v[12:13]
	v_pk_mul_f32 v[12:13], v[10:11], v[62:63] op_sel_hi:[0,1]
	v_pk_mul_f32 v[8:9], v[8:9], v[12:13]
	v_pk_mul_f32 v[12:13], v[10:11], v[60:61] op_sel_hi:[0,1]
	v_pk_mul_f32 v[2:3], v[2:3], v[12:13]
	v_pk_mul_f32 v[6:7], v[6:7], v[26:27]
	v_pk_mul_f32 v[12:13], v[2:3], v[32:33]
	v_pk_mul_f32 v[2:3], v[10:11], v[48:49] op_sel_hi:[0,1]
	v_pk_mul_f32 v[2:3], v[4:5], v[2:3]
	v_pk_mul_f32 v[8:9], v[8:9], v[34:35]
	v_pk_mul_f32 v[10:11], v[2:3], v[30:31]
	v_cvt_pk_bf16_f32 v2, v6, v7
	v_cvt_pk_bf16_f32 v3, v8, v9
	v_cvt_pk_bf16_f32 v4, v12, v13
	v_cvt_pk_bf16_f32 v5, v10, v11
	global_store_dwordx4 v[18:19], v[2:5], off
	s_barrier
.LBB0_701:
	s_add_i32 s96, s96, s32
	s_cmpk_lt_u32 s96, 0x200
	s_waitcnt vmcnt(63) expcnt(7) lgkmcnt(15)
	s_cbranch_scc0 .LBB0_753
